# v19 variant: all waiting workgroups poll the top-level arrival counter (reaches (round+1)*nx) instead of a generation word
# baseline (speedup 1.0000x reference)
.LBB0_86:
	s_lshl_b32 s0, s33, 8
	s_add_u32 s23, s36, s0
	s_addc_u32 s22, s37, 0
	v_mov_b32_e32 v1, s23
	v_add_co_u32_e32 v4, vcc, 0x1000, v1
	v_mov_b32_e32 v1, s22
	s_nop 0
	v_addc_co_u32_e32 v5, vcc, 0, v1, vcc
	v_mov_b32_e32 v1, 1
	flat_atomic_add v1, v[4:5], v1 offset:1024 sc0
	buffer_inv sc1
	v_cvt_f32_u32_e32 v3, v2
	v_sub_u32_e32 v4, 0, v2
	v_rcp_iflag_f32_e32 v3, v3
	s_nop 0
	v_mul_f32_e32 v3, 0x4f7ffffe, v3
	v_cvt_u32_f32_e32 v3, v3
	v_mul_lo_u32 v4, v4, v3
	v_mul_hi_u32 v4, v3, v4
	v_add_u32_e32 v3, v3, v4
	s_waitcnt vmcnt(1) lgkmcnt(0)
	v_mul_hi_u32 v3, v1, v3
	v_mul_lo_u32 v5, v3, v2
	v_add_u32_e32 v4, 1, v1
	v_sub_u32_e32 v1, v1, v5
	v_add_u32_e32 v6, 1, v3
	v_cmp_ge_u32_e32 vcc, v1, v2
	v_sub_u32_e32 v5, v1, v2
	s_nop 0
	v_cndmask_b32_e32 v3, v3, v6, vcc
	v_cndmask_b32_e32 v1, v1, v5, vcc
	v_add_u32_e32 v5, 1, v3
	v_cmp_ge_u32_e32 vcc, v1, v2
	s_nop 1
	v_cndmask_b32_e32 v1, v3, v5, vcc
	v_mad_u64_u32 v[2:3], s[0:1], v2, v1, v[2:3]
	v_cmp_ne_u32_e32 vcc, v4, v2
	s_and_saveexec_b64 s[0:1], vcc
	s_xor_b64 s[0:1], exec, s[0:1]
	s_cbranch_execz .LBB0_99
	v_mul_lo_u32 v4, v1, v0
	v_add_u32_e32 v4, v4, v0
	v_mov_b32_e32 v0, s36
	v_add_co_u32_e32 v2, vcc, 0x3000, v0
	v_mov_b32_e32 v0, s37
	s_nop 0
	v_addc_co_u32_e32 v3, vcc, 0, v0, vcc
	flat_load_dword v0, v[2:3] offset:1024 sc1
	s_add_u32 s6, s36, 0x3400
	s_addc_u32 s7, s37, 0
	s_waitcnt vmcnt(0) lgkmcnt(0)
	v_cmp_lt_u32_e32 vcc, v0, v4
	s_and_saveexec_b64 s[4:5], vcc
	s_cbranch_execz .LBB0_98
	s_mov_b32 s24, 1
	s_mov_b64 s[8:9], 0
	s_branch .LBB0_90

.LBB0_94:
	s_andn2_b64 s[12:13], s[12:13], exec
	s_and_b64 s[18:19], s[18:19], exec
	s_or_b64 s[12:13], s[12:13], s[18:19]
	s_and_saveexec_b64 s[18:19], s[16:17]
	s_cbranch_execz .LBB0_89
	v_mov_b64_e32 v[2:3], s[6:7]
	flat_load_dword v0, v[2:3] sc1
	s_add_i32 s24, s24, 1
	s_or_b64 s[12:13], s[12:13], exec
	s_waitcnt vmcnt(0) lgkmcnt(0)
	v_cmp_ge_u32_e32 vcc, v0, v4
	s_orn2_b64 s[14:15], vcc, exec
	s_branch .LBB0_89

.LBB0_99:
	s_andn2_saveexec_b64 s[0:1], s[0:1]
	s_cbranch_execz .LBB0_115
	v_mov_b32_e32 v1, s36
	v_add_co_u32_e32 v2, vcc, 0x3000, v1
	v_mov_b32_e32 v1, s37
	buffer_wbl2 sc1
	s_waitcnt vmcnt(0)
	v_addc_co_u32_e32 v3, vcc, 0, v1, vcc
	v_mov_b32_e32 v1, 1
	flat_atomic_add v1, v[2:3], v1 offset:1024 sc0
	v_cvt_f32_u32_e32 v2, v0
	v_sub_u32_e32 v3, 0, v0
	s_add_u32 s0, s36, 0x3500
	s_addc_u32 s1, s37, 0
	v_rcp_iflag_f32_e32 v2, v2
	s_mov_b64 s[6:7], -1
	v_mul_f32_e32 v2, 0x4f7ffffe, v2
	v_cvt_u32_f32_e32 v2, v2
	v_mul_lo_u32 v3, v3, v2
	v_mul_hi_u32 v3, v2, v3
	v_add_u32_e32 v2, v2, v3
	s_waitcnt vmcnt(0) lgkmcnt(0)
	v_mul_hi_u32 v2, v1, v2
	v_mul_lo_u32 v4, v2, v0
	v_add_u32_e32 v3, 1, v1
	v_sub_u32_e32 v1, v1, v4
	v_add_u32_e32 v5, 1, v2
	v_cmp_ge_u32_e32 vcc, v1, v0
	v_sub_u32_e32 v4, v1, v0
	s_nop 0
	v_cndmask_b32_e32 v2, v2, v5, vcc
	v_cndmask_b32_e32 v1, v1, v4, vcc
	v_add_u32_e32 v4, 1, v2
	v_cmp_ge_u32_e32 vcc, v1, v0
	s_nop 1
	v_cndmask_b32_e32 v2, v2, v4, vcc
	v_mad_u64_u32 v[0:1], s[4:5], v0, v2, v[0:1]
	v_cmp_ne_u32_e32 vcc, v3, v0
	v_mov_b32_e32 v4, v0
	v_mov_b64_e32 v[0:1], s[0:1]
	s_and_saveexec_b64 s[4:5], vcc
	s_cbranch_execz .LBB0_112
	v_mov_b64_e32 v[0:1], s[0:1]
	v_subrev_u32_e32 v0, 0x100, v0
	flat_load_dword v0, v[0:1] sc1
	s_mov_b64 s[10:11], 0
	s_waitcnt vmcnt(0) lgkmcnt(0)
	v_cmp_lt_u32_e32 vcc, v0, v4
	s_and_saveexec_b64 s[8:9], vcc
	s_cbranch_execz .LBB0_111
	s_add_u32 s6, s36, 0x200
	s_addc_u32 s7, s37, 0
	s_mov_b32 s24, 1
	s_branch .LBB0_104

.LBB0_109:
	v_mov_b64_e32 v[0:1], s[0:1]
	v_subrev_u32_e32 v0, 0x100, v0
	flat_load_dword v0, v[0:1] sc1
	s_add_i32 s24, s24, 1
	s_or_b64 s[14:15], s[14:15], exec
	s_waitcnt vmcnt(0) lgkmcnt(0)
	v_cmp_ge_u32_e32 vcc, v0, v4
	s_orn2_b64 s[18:19], vcc, exec
	s_branch .LBB0_103

.LBB0_237:
	v_readlane_b32 s4, v255, 5
	s_lshl_b32 s4, s4, 2
	s_add_u32 s19, s22, s4
	s_addc_u32 s17, s23, 0
	v_mov_b32_e32 v1, s19
	v_add_co_u32_e32 v4, vcc, 0x1000, v1
	v_mov_b32_e32 v1, s17
	s_nop 0
	v_addc_co_u32_e32 v5, vcc, 0, v1, vcc
	flat_atomic_add v3, v[4:5], v230 offset:1024 sc0
	buffer_inv sc1
	v_cvt_f32_u32_e32 v1, v2
	v_sub_u32_e32 v4, 0, v2
	v_rcp_iflag_f32_e32 v1, v1
	s_nop 0
	v_mul_f32_e32 v1, 0x4f7ffffe, v1
	v_cvt_u32_f32_e32 v1, v1
	v_mul_lo_u32 v4, v4, v1
	v_mul_hi_u32 v4, v1, v4
	v_add_u32_e32 v1, v1, v4
	s_waitcnt vmcnt(1) lgkmcnt(0)
	v_mul_hi_u32 v1, v3, v1
	v_mul_lo_u32 v4, v1, v2
	v_sub_u32_e32 v4, v3, v4
	v_cmp_ge_u32_e32 vcc, v4, v2
	v_add_u32_e32 v5, 1, v1
	s_nop 0
	v_cndmask_b32_e32 v1, v1, v5, vcc
	v_sub_u32_e32 v5, v4, v2
	v_cndmask_b32_e32 v4, v4, v5, vcc
	v_cmp_ge_u32_e32 vcc, v4, v2
	v_add_u32_e32 v4, 1, v1
	s_nop 0
	v_cndmask_b32_e32 v1, v1, v4, vcc
	v_add_u32_e32 v4, 1, v3
	v_mad_u64_u32 v[2:3], s[4:5], v2, v1, v[2:3]
	v_cmp_ne_u32_e32 vcc, v4, v2
	s_and_saveexec_b64 s[4:5], vcc
	s_xor_b64 s[4:5], exec, s[4:5]
	s_cbranch_execz .LBB0_250
	v_mul_lo_u32 v4, v1, v0
	v_add_u32_e32 v4, v4, v0
	v_mov_b32_e32 v0, s22
	v_add_co_u32_e32 v2, vcc, 0x3000, v0
	v_mov_b32_e32 v0, s23
	s_nop 0
	v_addc_co_u32_e32 v3, vcc, 0, v0, vcc
	flat_load_dword v0, v[2:3] offset:1024 sc1
	s_add_u32 s26, s22, 0x3400
	s_addc_u32 s27, s23, 0
	s_waitcnt vmcnt(0) lgkmcnt(0)
	v_cmp_lt_u32_e32 vcc, v0, v4
	s_and_saveexec_b64 s[24:25], vcc
	s_cbranch_execz .LBB0_249
	s_mov_b32 s44, 1
	s_mov_b64 s[28:29], 0
	s_branch .LBB0_241

.LBB0_245:
	s_andn2_b64 s[34:35], s[34:35], exec
	s_and_b64 s[40:41], s[40:41], exec
	s_or_b64 s[34:35], s[34:35], s[40:41]
	s_and_saveexec_b64 s[40:41], s[38:39]
	s_cbranch_execz .LBB0_240
	v_mov_b64_e32 v[2:3], s[26:27]
	flat_load_dword v0, v[2:3] sc1
	s_add_i32 s44, s44, 1
	s_or_b64 s[34:35], s[34:35], exec
	s_waitcnt vmcnt(0) lgkmcnt(0)
	v_cmp_ge_u32_e32 vcc, v0, v4
	s_orn2_b64 s[36:37], vcc, exec
	s_branch .LBB0_240

.LBB0_250:
	s_andn2_saveexec_b64 s[4:5], s[4:5]
	s_cbranch_execz .LBB0_266
	v_mov_b32_e32 v1, s22
	v_add_co_u32_e32 v2, vcc, 0x3000, v1
	v_mov_b32_e32 v1, s23
	buffer_wbl2 sc1
	s_waitcnt vmcnt(0)
	v_addc_co_u32_e32 v3, vcc, 0, v1, vcc
	flat_atomic_add v1, v[2:3], v230 offset:1024 sc0
	v_cvt_f32_u32_e32 v2, v0
	v_sub_u32_e32 v3, 0, v0
	s_mov_b64 s[26:27], -1
	v_rcp_iflag_f32_e32 v2, v2
	s_nop 0
	v_mul_f32_e32 v2, 0x4f7ffffe, v2
	v_cvt_u32_f32_e32 v2, v2
	v_mul_lo_u32 v3, v3, v2
	v_mul_hi_u32 v3, v2, v3
	v_add_u32_e32 v2, v2, v3
	s_waitcnt vmcnt(0) lgkmcnt(0)
	v_mul_hi_u32 v2, v1, v2
	v_mul_lo_u32 v3, v2, v0
	v_sub_u32_e32 v3, v1, v3
	v_cmp_ge_u32_e32 vcc, v3, v0
	v_add_u32_e32 v4, 1, v2
	s_nop 0
	v_cndmask_b32_e32 v2, v2, v4, vcc
	v_sub_u32_e32 v4, v3, v0
	v_cndmask_b32_e32 v3, v3, v4, vcc
	v_cmp_ge_u32_e32 vcc, v3, v0
	v_add_u32_e32 v3, 1, v2
	s_nop 0
	v_cndmask_b32_e32 v2, v2, v3, vcc
	v_add_u32_e32 v3, 1, v1
	v_mad_u64_u32 v[0:1], s[4:5], v0, v2, v[0:1]
	s_add_u32 s4, s22, 0x3500
	s_addc_u32 s5, s23, 0
	v_cmp_ne_u32_e32 vcc, v3, v0
	v_mov_b32_e32 v4, v0
	v_mov_b64_e32 v[0:1], s[4:5]
	s_and_saveexec_b64 s[24:25], vcc
	s_cbranch_execz .LBB0_263
	v_mov_b64_e32 v[0:1], s[4:5]
	v_subrev_u32_e32 v0, 0x100, v0
	flat_load_dword v0, v[0:1] sc1
	s_mov_b64 s[30:31], 0
	s_waitcnt vmcnt(0) lgkmcnt(0)
	v_cmp_lt_u32_e32 vcc, v0, v4
	s_and_saveexec_b64 s[28:29], vcc
	s_cbranch_execz .LBB0_262
	s_add_u32 s26, s22, 0x200
	s_addc_u32 s27, s23, 0
	s_mov_b32 s42, 1
	s_mov_b64 s[22:23], 0
	s_branch .LBB0_255

.LBB0_260:
	v_mov_b64_e32 v[0:1], s[4:5]
	v_subrev_u32_e32 v0, 0x100, v0
	flat_load_dword v0, v[0:1] sc1
	s_add_i32 s42, s42, 1
	s_or_b64 s[36:37], s[36:37], exec
	s_waitcnt vmcnt(0) lgkmcnt(0)
	v_cmp_ge_u32_e32 vcc, v0, v4
	s_orn2_b64 s[34:35], vcc, exec
	s_branch .LBB0_254

.LBB0_515:
	v_readlane_b32 s4, v255, 5
	s_lshl_b32 s4, s4, 2
	s_add_u32 s18, s20, s4
	s_addc_u32 s17, s21, 0
	v_mov_b32_e32 v1, s18
	v_add_co_u32_e32 v4, vcc, 0x1000, v1
	v_mov_b32_e32 v1, s17
	s_nop 0
	v_addc_co_u32_e32 v5, vcc, 0, v1, vcc
	flat_atomic_add v3, v[4:5], v230 offset:1024 sc0
	buffer_inv sc1
	v_cvt_f32_u32_e32 v1, v2
	v_sub_u32_e32 v4, 0, v2
	v_rcp_iflag_f32_e32 v1, v1
	s_nop 0
	v_mul_f32_e32 v1, 0x4f7ffffe, v1
	v_cvt_u32_f32_e32 v1, v1
	v_mul_lo_u32 v4, v4, v1
	v_mul_hi_u32 v4, v1, v4
	v_add_u32_e32 v1, v1, v4
	s_waitcnt vmcnt(1) lgkmcnt(0)
	v_mul_hi_u32 v1, v3, v1
	v_mul_lo_u32 v4, v1, v2
	v_sub_u32_e32 v4, v3, v4
	v_cmp_ge_u32_e32 vcc, v4, v2
	v_add_u32_e32 v5, 1, v1
	s_nop 0
	v_cndmask_b32_e32 v1, v1, v5, vcc
	v_sub_u32_e32 v5, v4, v2
	v_cndmask_b32_e32 v4, v4, v5, vcc
	v_cmp_ge_u32_e32 vcc, v4, v2
	v_add_u32_e32 v4, 1, v1
	s_nop 0
	v_cndmask_b32_e32 v1, v1, v4, vcc
	v_add_u32_e32 v4, 1, v3
	v_mad_u64_u32 v[2:3], s[4:5], v2, v1, v[2:3]
	v_cmp_ne_u32_e32 vcc, v4, v2
	s_and_saveexec_b64 s[4:5], vcc
	s_xor_b64 s[4:5], exec, s[4:5]
	s_cbranch_execz .LBB0_528
	v_mul_lo_u32 v4, v1, v0
	v_add_u32_e32 v4, v4, v0
	v_mov_b32_e32 v0, s20
	v_add_co_u32_e32 v2, vcc, 0x3000, v0
	v_mov_b32_e32 v0, s21
	s_nop 0
	v_addc_co_u32_e32 v3, vcc, 0, v0, vcc
	flat_load_dword v0, v[2:3] offset:1024 sc1
	s_add_u32 s24, s20, 0x3400
	s_addc_u32 s25, s21, 0
	s_waitcnt vmcnt(0) lgkmcnt(0)
	v_cmp_lt_u32_e32 vcc, v0, v4
	s_and_saveexec_b64 s[22:23], vcc
	s_cbranch_execz .LBB0_527
	s_mov_b32 s19, 1
	s_mov_b64 s[26:27], 0
	s_branch .LBB0_519

.LBB0_523:
	s_andn2_b64 s[30:31], s[30:31], exec
	s_and_b64 s[38:39], s[38:39], exec
	s_or_b64 s[30:31], s[30:31], s[38:39]
	s_and_saveexec_b64 s[38:39], s[36:37]
	s_cbranch_execz .LBB0_518
	v_mov_b64_e32 v[2:3], s[24:25]
	flat_load_dword v0, v[2:3] sc1
	s_add_i32 s19, s19, 1
	s_or_b64 s[30:31], s[30:31], exec
	s_waitcnt vmcnt(0) lgkmcnt(0)
	v_cmp_ge_u32_e32 vcc, v0, v4
	s_orn2_b64 s[34:35], vcc, exec
	s_branch .LBB0_518

.LBB0_528:
	s_andn2_saveexec_b64 s[4:5], s[4:5]
	s_cbranch_execz .LBB0_544
	v_mov_b32_e32 v1, s20
	v_add_co_u32_e32 v2, vcc, 0x3000, v1
	v_mov_b32_e32 v1, s21
	buffer_wbl2 sc1
	s_waitcnt vmcnt(0)
	v_addc_co_u32_e32 v3, vcc, 0, v1, vcc
	flat_atomic_add v1, v[2:3], v230 offset:1024 sc0
	v_cvt_f32_u32_e32 v2, v0
	v_sub_u32_e32 v3, 0, v0
	s_mov_b64 s[24:25], -1
	v_rcp_iflag_f32_e32 v2, v2
	s_nop 0
	v_mul_f32_e32 v2, 0x4f7ffffe, v2
	v_cvt_u32_f32_e32 v2, v2
	v_mul_lo_u32 v3, v3, v2
	v_mul_hi_u32 v3, v2, v3
	v_add_u32_e32 v2, v2, v3
	s_waitcnt vmcnt(0) lgkmcnt(0)
	v_mul_hi_u32 v2, v1, v2
	v_mul_lo_u32 v3, v2, v0
	v_sub_u32_e32 v3, v1, v3
	v_cmp_ge_u32_e32 vcc, v3, v0
	v_add_u32_e32 v4, 1, v2
	s_nop 0
	v_cndmask_b32_e32 v2, v2, v4, vcc
	v_sub_u32_e32 v4, v3, v0
	v_cndmask_b32_e32 v3, v3, v4, vcc
	v_cmp_ge_u32_e32 vcc, v3, v0
	v_add_u32_e32 v3, 1, v2
	s_nop 0
	v_cndmask_b32_e32 v2, v2, v3, vcc
	v_add_u32_e32 v3, 1, v1
	v_mad_u64_u32 v[0:1], s[4:5], v0, v2, v[0:1]
	s_add_u32 s4, s20, 0x3500
	s_addc_u32 s5, s21, 0
	v_cmp_ne_u32_e32 vcc, v3, v0
	v_mov_b32_e32 v4, v0
	v_mov_b64_e32 v[0:1], s[4:5]
	s_and_saveexec_b64 s[22:23], vcc
	s_cbranch_execz .LBB0_541
	v_mov_b64_e32 v[0:1], s[4:5]
	v_subrev_u32_e32 v0, 0x100, v0
	flat_load_dword v0, v[0:1] sc1
	s_mov_b64 s[28:29], 0
	s_waitcnt vmcnt(0) lgkmcnt(0)
	v_cmp_lt_u32_e32 vcc, v0, v4
	s_and_saveexec_b64 s[26:27], vcc
	s_cbranch_execz .LBB0_540
	s_add_u32 s24, s20, 0x200
	s_addc_u32 s25, s21, 0
	s_mov_b32 s19, 1
	s_mov_b64 s[20:21], 0
	s_branch .LBB0_533

.LBB0_538:
	v_mov_b64_e32 v[0:1], s[4:5]
	v_subrev_u32_e32 v0, 0x100, v0
	flat_load_dword v0, v[0:1] sc1
	s_add_i32 s19, s19, 1
	s_or_b64 s[34:35], s[34:35], exec
	s_waitcnt vmcnt(0) lgkmcnt(0)
	v_cmp_ge_u32_e32 vcc, v0, v4
	s_orn2_b64 s[30:31], vcc, exec
	s_branch .LBB0_532

.LBB0_809:
	v_readlane_b32 s4, v255, 5
	s_lshl_b32 s4, s4, 2
	s_add_u32 s39, s16, s4
	s_addc_u32 s38, s17, 0
	v_mov_b32_e32 v1, s39
	v_add_co_u32_e32 v4, vcc, 0x1000, v1
	v_mov_b32_e32 v1, s38
	s_nop 0
	v_addc_co_u32_e32 v5, vcc, 0, v1, vcc
	flat_atomic_add v3, v[4:5], v230 offset:1024 sc0
	buffer_inv sc1
	v_cvt_f32_u32_e32 v1, v2
	v_sub_u32_e32 v4, 0, v2
	v_rcp_iflag_f32_e32 v1, v1
	s_nop 0
	v_mul_f32_e32 v1, 0x4f7ffffe, v1
	v_cvt_u32_f32_e32 v1, v1
	v_mul_lo_u32 v4, v4, v1
	v_mul_hi_u32 v4, v1, v4
	v_add_u32_e32 v1, v1, v4
	s_waitcnt vmcnt(1) lgkmcnt(0)
	v_mul_hi_u32 v1, v3, v1
	v_mul_lo_u32 v4, v1, v2
	v_sub_u32_e32 v4, v3, v4
	v_cmp_ge_u32_e32 vcc, v4, v2
	v_add_u32_e32 v5, 1, v1
	s_nop 0
	v_cndmask_b32_e32 v1, v1, v5, vcc
	v_sub_u32_e32 v5, v4, v2
	v_cndmask_b32_e32 v4, v4, v5, vcc
	v_cmp_ge_u32_e32 vcc, v4, v2
	v_add_u32_e32 v4, 1, v1
	s_nop 0
	v_cndmask_b32_e32 v1, v1, v4, vcc
	v_add_u32_e32 v4, 1, v3
	v_mad_u64_u32 v[2:3], s[4:5], v2, v1, v[2:3]
	v_cmp_ne_u32_e32 vcc, v4, v2
	s_and_saveexec_b64 s[4:5], vcc
	s_xor_b64 s[4:5], exec, s[4:5]
	s_cbranch_execz .LBB0_822
	v_mul_lo_u32 v4, v1, v0
	v_add_u32_e32 v4, v4, v0
	v_mov_b32_e32 v0, s16
	v_add_co_u32_e32 v2, vcc, 0x3000, v0
	v_mov_b32_e32 v0, s17
	s_nop 0
	v_addc_co_u32_e32 v3, vcc, 0, v0, vcc
	flat_load_dword v0, v[2:3] offset:1024 sc1
	s_add_u32 s20, s16, 0x3400
	s_addc_u32 s21, s17, 0
	s_waitcnt vmcnt(0) lgkmcnt(0)
	v_cmp_lt_u32_e32 vcc, v0, v4
	s_and_saveexec_b64 s[18:19], vcc
	s_cbranch_execz .LBB0_821
	s_mov_b32 s40, 1
	s_mov_b64 s[22:23], 0
	s_branch .LBB0_813

.LBB0_817:
	s_andn2_b64 s[26:27], s[26:27], exec
	s_and_b64 s[34:35], s[34:35], exec
	s_or_b64 s[26:27], s[26:27], s[34:35]
	s_and_saveexec_b64 s[34:35], s[30:31]
	s_cbranch_execz .LBB0_812
	v_mov_b64_e32 v[2:3], s[20:21]
	flat_load_dword v0, v[2:3] sc1
	s_add_i32 s40, s40, 1
	s_or_b64 s[26:27], s[26:27], exec
	s_waitcnt vmcnt(0) lgkmcnt(0)
	v_cmp_ge_u32_e32 vcc, v0, v4
	s_orn2_b64 s[28:29], vcc, exec
	s_branch .LBB0_812

.LBB0_822:
	s_andn2_saveexec_b64 s[4:5], s[4:5]
	s_cbranch_execz .LBB0_118
	v_mov_b32_e32 v1, s16
	v_add_co_u32_e32 v2, vcc, 0x3000, v1
	v_mov_b32_e32 v1, s17
	buffer_wbl2 sc1
	s_waitcnt vmcnt(0)
	v_addc_co_u32_e32 v3, vcc, 0, v1, vcc
	flat_atomic_add v1, v[2:3], v230 offset:1024 sc0
	v_cvt_f32_u32_e32 v2, v0
	v_sub_u32_e32 v3, 0, v0
	s_mov_b64 s[20:21], -1
	v_rcp_iflag_f32_e32 v2, v2
	s_nop 0
	v_mul_f32_e32 v2, 0x4f7ffffe, v2
	v_cvt_u32_f32_e32 v2, v2
	v_mul_lo_u32 v3, v3, v2
	v_mul_hi_u32 v3, v2, v3
	v_add_u32_e32 v2, v2, v3
	s_waitcnt vmcnt(0) lgkmcnt(0)
	v_mul_hi_u32 v2, v1, v2
	v_mul_lo_u32 v3, v2, v0
	v_sub_u32_e32 v3, v1, v3
	v_cmp_ge_u32_e32 vcc, v3, v0
	v_add_u32_e32 v4, 1, v2
	s_nop 0
	v_cndmask_b32_e32 v2, v2, v4, vcc
	v_sub_u32_e32 v4, v3, v0
	v_cndmask_b32_e32 v3, v3, v4, vcc
	v_cmp_ge_u32_e32 vcc, v3, v0
	v_add_u32_e32 v3, 1, v2
	s_nop 0
	v_cndmask_b32_e32 v2, v2, v3, vcc
	v_add_u32_e32 v3, 1, v1
	v_mad_u64_u32 v[0:1], s[4:5], v0, v2, v[0:1]
	s_add_u32 s4, s16, 0x3500
	s_addc_u32 s5, s17, 0
	v_cmp_ne_u32_e32 vcc, v3, v0
	v_mov_b32_e32 v4, v0
	v_mov_b64_e32 v[0:1], s[4:5]
	s_and_saveexec_b64 s[18:19], vcc
	s_cbranch_execz .LBB0_835
	v_mov_b64_e32 v[0:1], s[4:5]
	v_subrev_u32_e32 v0, 0x100, v0
	flat_load_dword v0, v[0:1] sc1
	s_mov_b64 s[24:25], 0
	s_waitcnt vmcnt(0) lgkmcnt(0)
	v_cmp_lt_u32_e32 vcc, v0, v4
	s_and_saveexec_b64 s[22:23], vcc
	s_cbranch_execz .LBB0_834
	s_add_u32 s20, s16, 0x200
	s_addc_u32 s21, s17, 0
	s_mov_b32 s36, 1
	s_mov_b64 s[16:17], 0
	s_branch .LBB0_827

.LBB0_832:
	v_mov_b64_e32 v[0:1], s[4:5]
	v_subrev_u32_e32 v0, 0x100, v0
	flat_load_dword v0, v[0:1] sc1
	s_add_i32 s36, s36, 1
	s_or_b64 s[28:29], s[28:29], exec
	s_waitcnt vmcnt(0) lgkmcnt(0)
	v_cmp_ge_u32_e32 vcc, v0, v4
	s_orn2_b64 s[26:27], vcc, exec
	s_branch .LBB0_826
